# baseline (speedup 1.0000x reference)
; DEV void phase_ml_in(const Params& p, unsigned char* smem) {
;     ...
;   for (int t = blockIdx.x; t < ntile; t += gridDim.x) {
;     int nt = t % 25, mt = t / 25;
;     const bf16_t* A = p.hbuf + (size_t)mt * 128 * 1024;
;     if (nt < 8 || (nt >= 16 && nt < 24)) {
;       bf16_t* obase = nt < 8 ? p.qb : p.ob - 2048;
.LBB0_845:
	s_and_b32 s0, s57, 7
	s_mul_i32 s1, s0, 0x19c
	s_min_u32 s0, s0, 4
	s_add_i32 s1, s1, s0
	s_lshr_b32 s0, s57, 3
	s_add_i32 s22, s1, s0
	s_cmpk_lt_u32 s22, 0xc80
	s_cbranch_scc0 .Lmlin_tail_grp
	s_lshr_b32 s0, s22, 4
	s_mul_hi_i32 s0, s0, 0x51eb851f
	s_ashr_i32 s0, s0, 3
	s_mul_i32 s1, s0, 0x190
	s_sub_i32 s1, s22, s1
	s_lshl_b32 s20, s0, 4
	s_and_b32 s0, s1, 15
	s_add_i32 s20, s20, s0
	s_lshr_b32 s22, s1, 4
	s_branch .Lmlin_grp_done
